# attn inst1: rescale-reference check via scalar flag, QK and first PV-group lgkmcnt ladders shortened (-7 instrs/tile)
# baseline (speedup 1.0000x reference)
; #define LAS __attribute__((address_space(3)))
; #define EXPALL(PF) do { _Pragma("unroll") for (int s_ = 0; s_ < 16 * NQT; ++s_) EXP1(s_); PACK16(PF, 0, 0); PACK16(PF, 0, 1); if (NQT > 1) { PACK16(PF, 1, 0); PACK16(PF, 1, 1); } } while (0)
; template <bool SAMPLE> __device__ __forceinline__ void attn_unit16(const Ctx& c, LAS unsigned char* lds, int b, int h, int qb, int wave_s) {
;     ...
;     if (SAMPLE) { load_kv(0, true); load_kv(0, false); store_k(0); store_v(0); load_kv(1, true); store_k(1); }
;     else { load_kv(0, true); const u32x4 k0a = kreg[0], k0b = kreg[1];
;       load_kv(0, false); load_kv(1, true);
;       LAS unsigned char* kb0 = lds + lrow * A_RSK + lck * 16; *(LAS u32x4*)kb0 = k0a; *(LAS u32x4*)(kb0 + 128) = k0b;
;       store_v(0); store_k(1); }
;     __syncthreads();
;     if (active) { QK16(0); MAX16(0); EXPALL(pfa); }
.LBB0_832:
	s_or_b64 exec, exec, s[0:1]
	s_lshr_b32 s56, s45, 2
	s_bfe_u32 s0, s51, 0x20007
	s_ashr_i32 s16, s44, 3
	s_xor_b32 s2, s56, 63
	s_xor_b32 s63, s0, 2
	s_lshl_b32 s0, s2, 7
	s_lshl_b32 s1, s63, 5
	s_ashr_i32 s17, s16, 31
	s_or_b32 s86, s1, s0
	s_lshl_b64 s[16:17], s[16:17], 13
	s_bfe_u32 s81, s51, 0x10006
	s_or_b32 s62, s16, s86
	s_lshl_b32 s3, s80, 8
	s_add_u32 s40, s92, s3
	s_addc_u32 s41, s93, 0
	s_lshl_b32 s3, s81, 7
	v_bfe_u32 v210, v44, 4, 2
	s_add_u32 s42, s40, s3
	v_ashrrev_i32_e32 v2, 3, v44
	s_addc_u32 s43, s41, 0
	v_lshlrev_b32_e32 v0, 4, v210
	v_ashrrev_i32_e32 v3, 31, v2
	v_lshl_add_u64 v[20:21], s[42:43], 0, v[0:1]
	v_mad_i64_i32 v[4:5], s[42:43], s44, v207, v[2:3]
	v_lshlrev_b64 v[4:5], 8, v[4:5]
	v_lshlrev_b32_e32 v10, 4, v44
	v_lshl_add_u64 v[6:7], s[4:5], 0, v[4:5]
	s_waitcnt vmcnt(2)
	v_and_b32_e32 v46, 0x70, v10
	v_mov_b32_e32 v47, v1
	v_lshl_add_u64 v[10:11], v[6:7], 0, v[46:47]
	v_and_b32_e32 v45, 15, v44
	global_load_dwordx4 v[36:39], v[10:11], off
	global_load_dwordx4 v[40:43], v[10:11], off offset:128
	v_lshl_add_u64 v[4:5], s[6:7], 0, v[4:5]
	v_add_co_u32_e32 v10, vcc, s69, v10
	v_or_b32_e32 v8, s62, v45
	v_mov_b32_e32 v9, s17
	v_lshl_add_u64 v[12:13], v[4:5], 0, v[46:47]
	v_addc_co_u32_e32 v11, vcc, 0, v11, vcc
	global_load_dwordx4 v[4:7], v[12:13], off
	s_nop 0
	global_load_dwordx4 v[12:15], v[12:13], off offset:128
	s_nop 0
	global_load_dwordx4 v[28:31], v[10:11], off
	global_load_dwordx4 v[32:35], v[10:11], off offset:128
	v_lshlrev_b64 v[22:23], 11, v[8:9]
	v_lshl_add_u64 v[16:17], v[20:21], 0, v[22:23]
	v_or_b32_e32 v22, 0x8000, v22
	v_lshl_add_u64 v[24:25], v[20:21], 0, v[22:23]
	global_load_dwordx4 v[8:11], v[16:17], off
	s_nop 0
	global_load_dwordx4 v[16:19], v[16:17], off offset:64
	s_nop 0
	global_load_dwordx4 v[20:23], v[24:25], off
	s_nop 0
	global_load_dwordx4 v[24:27], v[24:25], off offset:64
	v_mul_lo_u32 v47, v2, s70
	v_lshlrev_b32_e32 v48, 4, v2
	v_add_u32_e32 v47, 0, v47
	v_add_u32_e32 v211, v47, v46
	v_add_u32_e32 v47, v47, v48
	s_add_i32 s3, s3, 0
	v_add_u32_e32 v213, v47, v46
	s_waitcnt vmcnt(9)
	ds_write_b128 v211, v[36:39]
	s_waitcnt vmcnt(8)
	ds_write_b128 v211, v[40:43] offset:128
	s_waitcnt vmcnt(7)
	ds_write_b128 v213, v[4:7] offset:17408
	s_waitcnt vmcnt(6)
	ds_write_b128 v213, v[12:15] offset:17536
	s_waitcnt vmcnt(5)
	ds_write_b128 v211, v[28:31] offset:35840
	s_waitcnt vmcnt(4)
	ds_write_b128 v211, v[32:35] offset:35968
	v_mov_b32_e32 v36, s3
	v_mad_u32_u24 v36, v45, s70, v36
	v_add_u32_e32 v214, v36, v0
	s_waitcnt lgkmcnt(0)
	s_barrier
	ds_read_b128 v[36:39], v214
	ds_read_b128 v[40:43], v214 offset:64
	s_waitcnt vmcnt(3) lgkmcnt(1)
	v_mfma_f32_16x16x32_bf16 v[46:49], v[36:39], v[8:11], 0
	s_waitcnt vmcnt(1)
	v_mfma_f32_16x16x32_bf16 v[36:39], v[36:39], v[20:23], 0
	s_waitcnt lgkmcnt(0)
	v_mfma_f32_16x16x32_bf16 v[48:51], v[40:43], v[16:19], v[46:49]
	s_waitcnt vmcnt(0)
	v_mfma_f32_16x16x32_bf16 v[52:55], v[40:43], v[24:27], v[36:39]
	v_mov_b32_e32 v0, s71
	ds_read_b32 v0, v0
	v_mov_b32_e32 v46, 0xff800000
	s_waitcnt lgkmcnt(0)
	s_nop 1
	v_pk_add_f32 v[42:43], v[48:49], v[0:1] op_sel_hi:[1,0]
	v_pk_add_f32 v[40:41], v[50:51], v[0:1] op_sel_hi:[1,0]
	v_pk_add_f32 v[38:39], v[52:53], v[0:1] op_sel_hi:[1,0]
	v_pk_add_f32 v[36:37], v[54:55], v[0:1] op_sel_hi:[1,0]
	v_max3_f32 v0, v42, v43, v40
	v_max_f32_e32 v47, 0xff800000, v41
	v_max3_f32 v47, v0, v46, v47
	v_max3_f32 v0, v38, v39, v36
	v_max_f32_e32 v48, 0xff800000, v37
	v_max3_f32 v0, v0, v46, v48
	v_max_f32_e64 v48, |v47|, |v0|
	v_cmp_lt_f32_e32 vcc, s72, v48
	s_cbranch_vccz .LBB0_834
	s_mov_b32 s98, 1
	v_and_b32_e32 v48, 64, v212
	v_xor_b32_e32 v46, 16, v212
	v_add_u32_e32 v48, 64, v48
	v_cmp_lt_i32_e32 vcc, v46, v48
	v_xor_b32_e32 v49, 32, v212
	s_nop 0
	v_cndmask_b32_e32 v46, v212, v46, vcc
	v_lshlrev_b32_e32 v46, 2, v46
	ds_bpermute_b32 v50, v46, v47
	ds_bpermute_b32 v46, v46, v0
	v_cmp_lt_i32_e32 vcc, v49, v48
	v_max_f32_e32 v0, v0, v0
	v_max_f32_e32 v47, v47, v47
	v_cndmask_b32_e32 v48, v212, v49, vcc
	s_waitcnt lgkmcnt(0)
	v_max_f32_e32 v46, v46, v46
	v_lshlrev_b32_e32 v48, 2, v48
	v_max_f32_e32 v49, v50, v50
	v_max_f32_e32 v0, v0, v46
	v_max_f32_e32 v47, v47, v49
	ds_bpermute_b32 v46, v48, v0
	ds_bpermute_b32 v49, v48, v47
	s_waitcnt lgkmcnt(1)
	v_max_f32_e32 v46, v46, v46
	s_waitcnt lgkmcnt(0)
	v_max_f32_e32 v48, v49, v49
	v_max_f32_e32 v0, v0, v46
	v_max_f32_e32 v47, v47, v48
	v_cmp_gt_f32_e64 vcc, |v0|, s72
	s_nop 1
	v_cndmask_b32_e32 v197, 0, v0, vcc
	v_cmp_gt_f32_e64 vcc, |v47|, s72
	v_exp_f32_e64 v201, -v197
	v_sub_f32_e32 v0, 0xff800000, v197
	v_cndmask_b32_e32 v196, 0, v47, vcc
	v_exp_f32_e64 v200, -v196
	v_sub_f32_e32 v42, v42, v196
	v_sub_f32_e32 v43, v43, v196
	v_sub_f32_e32 v40, v40, v196
	v_sub_f32_e32 v41, v41, v196
	v_sub_f32_e32 v46, 0xff800000, v196
	v_sub_f32_e32 v38, v38, v197
	v_sub_f32_e32 v39, v39, v197
	v_sub_f32_e32 v36, v36, v197
	v_sub_f32_e32 v37, v37, v197
	v_mov_b32_e32 v47, v0
	v_mov_b32_e32 v48, v0
	v_mov_b32_e32 v49, v0
	s_branch .LBB0_835
.LBB0_834:
	s_mov_b32 s98, 0
	v_mov_b32_e32 v0, v1
	v_mov_b32_e32 v200, 1.0
	v_mov_b32_e32 v201, v200
	v_mov_b64_e32 v[196:197], v[0:1]
	v_mov_b32_e32 v0, 0xff800000
	v_mov_b32_e32 v47, 0xff800000
	v_mov_b32_e32 v48, 0xff800000
	v_mov_b32_e32 v49, 0xff800000

.LBB0_836:
	s_add_i32 s88, s89, 2
	s_cmp_lt_u32 s88, s84
	s_cbranch_scc0 .Lq1_last
	v_add_co_u32_e32 v2, vcc, 0xfbf00000, v202
	s_nop 1
	v_addc_co_u32_e32 v3, vcc, -1, v203, vcc
	global_load_dwordx4 v[28:31], v[2:3], off offset:-128
	global_load_dwordx4 v[32:35], v[2:3], off
	v_add_co_u32_e32 v2, vcc, 0xffffc000, v202
	s_nop 1
	v_addc_co_u32_e32 v3, vcc, -1, v203, vcc
	global_load_dwordx4 v[4:7], v[2:3], off offset:-128
	global_load_dwordx4 v[12:15], v[2:3], off
	ds_read_b128 v[44:47], v214 offset:35840
	ds_read_b128 v[72:75], v214 offset:35904
	ds_read_b128 v[92:95], v214 offset:40192
	ds_read_b128 v[112:115], v214 offset:40256
	ds_read_b128 v[132:135], v214 offset:44544
	ds_read_b128 v[148:151], v214 offset:44608
	ds_read_b128 v[136:139], v214 offset:48896
	ds_read_b128 v[152:155], v214 offset:48960
	s_waitcnt lgkmcnt(7)
	v_mfma_f32_16x16x32_bf16 v[140:143], v[44:47], v[8:11], 0
	v_mfma_f32_16x16x32_bf16 v[44:47], v[44:47], v[20:23], 0
	s_waitcnt lgkmcnt(1)
	v_mfma_f32_16x16x32_bf16 v[156:159], v[92:95], v[8:11], 0
	v_mfma_f32_16x16x32_bf16 v[92:95], v[92:95], v[20:23], 0
	v_mfma_f32_16x16x32_bf16 v[160:163], v[132:135], v[8:11], 0
	v_mfma_f32_16x16x32_bf16 v[132:135], v[132:135], v[20:23], 0
	v_mfma_f32_16x16x32_bf16 v[164:167], v[136:139], v[8:11], 0
	v_mfma_f32_16x16x32_bf16 v[168:171], v[136:139], v[20:23], 0
	v_mfma_f32_16x16x32_bf16 v[144:147], v[72:75], v[16:19], v[140:143]
	v_mfma_f32_16x16x32_bf16 v[136:139], v[72:75], v[24:27], v[44:47]
	v_mfma_f32_16x16x32_bf16 v[44:47], v[112:115], v[16:19], v[156:159]
	v_mfma_f32_16x16x32_bf16 v[92:95], v[112:115], v[24:27], v[92:95]
	v_mfma_f32_16x16x32_bf16 v[140:143], v[148:151], v[16:19], v[160:163]
	v_mfma_f32_16x16x32_bf16 v[132:135], v[148:151], v[24:27], v[132:135]
	s_waitcnt lgkmcnt(0)
	v_mfma_f32_16x16x32_bf16 v[72:75], v[152:155], v[16:19], v[164:167]
	v_mfma_f32_16x16x32_bf16 v[112:115], v[152:155], v[24:27], v[168:171]
	s_cmp_eq_u32 s98, 0
	s_cbranch_scc1 .LBB0_859
	v_sub_f32_e32 v147, v147, v196
	v_sub_f32_e32 v146, v146, v196
	v_sub_f32_e32 v145, v145, v196
	v_sub_f32_e32 v144, v144, v196
	v_sub_f32_e32 v47, v47, v196
	v_sub_f32_e32 v46, v46, v196
	v_sub_f32_e32 v45, v45, v196
	v_sub_f32_e32 v44, v44, v196
	v_sub_f32_e32 v143, v143, v196
	v_sub_f32_e32 v142, v142, v196
	v_sub_f32_e32 v141, v141, v196
	v_sub_f32_e32 v140, v140, v196
	v_sub_f32_e32 v75, v75, v196
	v_sub_f32_e32 v74, v74, v196
	v_sub_f32_e32 v73, v73, v196
	v_sub_f32_e32 v72, v72, v196
	v_sub_f32_e32 v139, v139, v197
	v_sub_f32_e32 v138, v138, v197
	v_sub_f32_e32 v137, v137, v197
	v_sub_f32_e32 v136, v136, v197
	v_sub_f32_e32 v95, v95, v197
	v_sub_f32_e32 v94, v94, v197
	v_sub_f32_e32 v93, v93, v197
	v_sub_f32_e32 v92, v92, v197
	v_sub_f32_e32 v135, v135, v197
	v_sub_f32_e32 v134, v134, v197
	v_sub_f32_e32 v133, v133, v197
	v_sub_f32_e32 v132, v132, v197
	v_sub_f32_e32 v115, v115, v197
	v_sub_f32_e32 v114, v114, v197
	v_sub_f32_e32 v113, v113, v197
	v_sub_f32_e32 v112, v112, v197

.LBB0_861:
	v_max_f32_e32 v0, v144, v145
	v_max3_f32 v2, v147, v44, v45
	v_max3_f32 v0, v0, v146, v46
	v_max3_f32 v2, v2, v140, v141
	v_max3_f32 v0, v0, v47, v142
	v_max3_f32 v2, v2, v72, v73
	v_max3_f32 v0, v0, v143, v74
	v_max3_f32 v0, v0, v75, v2
	v_max_f32_e32 v2, v136, v137
	v_max3_f32 v3, v139, v92, v93
	v_max3_f32 v2, v2, v138, v94
	v_max3_f32 v3, v3, v132, v133
	v_max3_f32 v2, v2, v95, v134
	v_max3_f32 v3, v3, v112, v113
	v_max3_f32 v2, v2, v135, v114
	v_max3_f32 v2, v2, v115, v3
	v_max_f32_e32 v3, v0, v2
	v_cmp_lt_f32_e32 vcc, s74, v3
	s_cmp_lg_u64 vcc, 0
	s_cselect_b64 s[0:1], -1, 0
	s_cbranch_vccz .LBB0_863
	s_mov_b32 s98, 1
	v_and_b32_e32 v148, 64, v212
	v_xor_b32_e32 v3, 16, v212
	v_add_u32_e32 v148, 64, v148
	v_cmp_lt_i32_e32 vcc, v3, v148
	v_xor_b32_e32 v149, 32, v212
	s_nop 0
	v_cndmask_b32_e32 v3, v212, v3, vcc
	v_lshlrev_b32_e32 v3, 2, v3
	ds_bpermute_b32 v150, v3, v0
	ds_bpermute_b32 v3, v3, v2
	v_cmp_lt_i32_e32 vcc, v149, v148
	v_max_f32_e32 v2, v2, v2
	v_max_f32_e32 v0, v0, v0
	v_cndmask_b32_e32 v148, v212, v149, vcc
	s_waitcnt lgkmcnt(0)
	v_max_f32_e32 v3, v3, v3
	v_lshlrev_b32_e32 v148, 2, v148
	v_max_f32_e32 v149, v150, v150
	v_max_f32_e32 v2, v2, v3
	v_max_f32_e32 v0, v0, v149
	ds_bpermute_b32 v3, v148, v2
	ds_bpermute_b32 v149, v148, v0
	s_waitcnt lgkmcnt(1)
	v_max_f32_e32 v3, v3, v3
	s_waitcnt lgkmcnt(0)
	v_max_f32_e32 v148, v149, v149
	v_max_f32_e32 v2, v2, v3
	v_max_f32_e32 v0, v0, v148
	v_cmp_lt_f32_e32 vcc, s74, v2
	s_nop 1
	v_cndmask_b32_e32 v3, 0, v2, vcc
	v_cmp_lt_f32_e32 vcc, s74, v0
	v_exp_f32_e64 v201, -v3
	v_sub_f32_e32 v136, v136, v3
	v_cndmask_b32_e32 v2, 0, v0, vcc
	v_exp_f32_e64 v200, -v2
	v_sub_f32_e32 v144, v144, v2
	v_sub_f32_e32 v145, v145, v2
	v_sub_f32_e32 v146, v146, v2
	v_sub_f32_e32 v147, v147, v2
	v_sub_f32_e32 v44, v44, v2
	v_sub_f32_e32 v45, v45, v2
	v_sub_f32_e32 v46, v46, v2
	v_sub_f32_e32 v47, v47, v2
	v_sub_f32_e32 v140, v140, v2
	v_sub_f32_e32 v141, v141, v2
	v_sub_f32_e32 v142, v142, v2
	v_sub_f32_e32 v143, v143, v2
	v_sub_f32_e32 v72, v72, v2
	v_sub_f32_e32 v73, v73, v2
	v_sub_f32_e32 v74, v74, v2
	v_sub_f32_e32 v75, v75, v2
	v_pk_add_f32 v[196:197], v[196:197], v[2:3]
	v_sub_f32_e32 v137, v137, v3
	v_sub_f32_e32 v138, v138, v3
	v_sub_f32_e32 v139, v139, v3
	v_sub_f32_e32 v92, v92, v3
	v_sub_f32_e32 v93, v93, v3
	v_sub_f32_e32 v94, v94, v3
	v_sub_f32_e32 v95, v95, v3
	v_sub_f32_e32 v132, v132, v3
	v_sub_f32_e32 v133, v133, v3
	v_sub_f32_e32 v134, v134, v3
	v_sub_f32_e32 v135, v135, v3
	v_sub_f32_e32 v112, v112, v3
	v_sub_f32_e32 v113, v113, v3
	v_sub_f32_e32 v114, v114, v3
	v_sub_f32_e32 v115, v115, v3
	v_pk_mul_f32 v[198:199], v[198:199], v[200:201]
.LBB0_863:
	ds_read_b64_tr_b16 v[148:149], v215 offset:17408
	ds_read_b64_tr_b16 v[152:153], v215 offset:17440
	ds_read_b64_tr_b16 v[156:157], v215 offset:17472
	ds_read_b64_tr_b16 v[160:161], v215 offset:17504
	ds_read_b64_tr_b16 v[150:151], v215 offset:22016
	ds_read_b64_tr_b16 v[154:155], v215 offset:22048
	ds_read_b64_tr_b16 v[158:159], v215 offset:22080
	ds_read_b64_tr_b16 v[162:163], v215 offset:22112
	v_exp_f32_e32 v2, v144
	s_waitcnt lgkmcnt(3)
	v_mfma_f32_16x16x32_bf16 v[164:167], v[36:39], v[148:151], v[128:131]
	v_exp_f32_e32 v222, v145
	v_mfma_f32_16x16x32_bf16 v[148:151], v[60:63], v[148:151], v[120:123]
	ds_read_b64_tr_b16 v[238:239], v215 offset:17536
	ds_read_b64_tr_b16 v[242:243], v215 offset:17568
	ds_read_b64_tr_b16 v[246:247], v215 offset:17600
	ds_read_b64_tr_b16 v[250:251], v215 offset:17632
	ds_read_b64_tr_b16 v[240:241], v215 offset:22144
	ds_read_b64_tr_b16 v[244:245], v215 offset:22176
	ds_read_b64_tr_b16 v[248:249], v215 offset:22208
	ds_read_b64_tr_b16 v[252:253], v215 offset:22240
	v_exp_f32_e32 v224, v146
	s_waitcnt lgkmcnt(8)
	v_mfma_f32_16x16x32_bf16 v[124:127], v[36:39], v[152:155], v[124:127]
	v_exp_f32_e32 v122, v147
	v_mfma_f32_16x16x32_bf16 v[152:155], v[60:63], v[152:155], v[108:111]
	v_exp_f32_e32 v226, v44
	v_mfma_f32_16x16x32_bf16 v[116:119], v[36:39], v[156:159], v[116:119]
	v_exp_f32_e32 v110, v45
	v_mfma_f32_16x16x32_bf16 v[168:171], v[60:63], v[156:159], v[100:103]
	v_exp_f32_e32 v228, v46
	v_mfma_f32_16x16x32_bf16 v[104:107], v[36:39], v[160:163], v[104:107]
	v_exp_f32_e32 v100, v47
	v_mfma_f32_16x16x32_bf16 v[160:163], v[60:63], v[160:163], v[96:99]
	v_cvt_pk_bf16_f32 v44, v2, v222
	v_cvt_pk_bf16_f32 v45, v224, v122
	v_cvt_pk_bf16_f32 v46, v226, v110
	v_cvt_pk_bf16_f32 v47, v228, v100
	v_exp_f32_e32 v96, v140
	s_waitcnt lgkmcnt(0)
	v_mfma_f32_16x16x32_bf16 v[180:183], v[36:39], v[238:241], v[88:91]
	v_exp_f32_e32 v230, v141
	v_mfma_f32_16x16x32_bf16 v[184:187], v[60:63], v[238:241], v[76:79]
	v_exp_f32_e32 v232, v142
	v_mfma_f32_16x16x32_bf16 v[80:83], v[36:39], v[242:245], v[80:83]
	v_exp_f32_e32 v78, v143
	v_mfma_f32_16x16x32_bf16 v[188:191], v[60:63], v[242:245], v[64:67]
	ds_read_b64_tr_b16 v[140:141], v215 offset:26624
	ds_read_b64_tr_b16 v[156:157], v215 offset:26656
	ds_read_b64_tr_b16 v[172:173], v215 offset:26688
	ds_read_b64_tr_b16 v[176:177], v215 offset:26720
	ds_read_b64_tr_b16 v[142:143], v215 offset:31232
	ds_read_b64_tr_b16 v[158:159], v215 offset:31264
	ds_read_b64_tr_b16 v[174:175], v215 offset:31296
	ds_read_b64_tr_b16 v[178:179], v215 offset:31328
	v_exp_f32_e32 v234, v72
	v_mfma_f32_16x16x32_bf16 v[68:71], v[36:39], v[246:249], v[68:71]
	v_exp_f32_e32 v66, v73
	v_mfma_f32_16x16x32_bf16 v[192:195], v[60:63], v[246:249], v[52:55]
	v_exp_f32_e32 v236, v74
	v_mfma_f32_16x16x32_bf16 v[56:59], v[36:39], v[250:253], v[56:59]
	v_exp_f32_e32 v54, v75
	v_mfma_f32_16x16x32_bf16 v[48:51], v[60:63], v[250:253], v[48:51]
	v_cvt_pk_bf16_f32 v72, v96, v230
	v_cvt_pk_bf16_f32 v73, v232, v78
	v_cvt_pk_bf16_f32 v74, v234, v66
	v_cvt_pk_bf16_f32 v75, v236, v54
	v_exp_f32_e32 v3, v136
	s_waitcnt lgkmcnt(0)
	v_mfma_f32_16x16x32_bf16 v[144:147], v[40:43], v[140:143], v[164:167]
	v_exp_f32_e32 v223, v137
	v_mfma_f32_16x16x32_bf16 v[140:143], v[84:87], v[140:143], v[148:151]
	ds_read_b64_tr_b16 v[238:239], v215 offset:26752
	ds_read_b64_tr_b16 v[242:243], v215 offset:26784
	ds_read_b64_tr_b16 v[246:247], v215 offset:26816
	ds_read_b64_tr_b16 v[250:251], v215 offset:26848
	ds_read_b64_tr_b16 v[240:241], v215 offset:31360
	ds_read_b64_tr_b16 v[244:245], v215 offset:31392
	ds_read_b64_tr_b16 v[248:249], v215 offset:31424
	ds_read_b64_tr_b16 v[252:253], v215 offset:31456
	v_exp_f32_e32 v225, v138
	v_mfma_f32_16x16x32_bf16 v[148:151], v[40:43], v[156:159], v[124:127]
	v_exp_f32_e32 v123, v139
	v_mfma_f32_16x16x32_bf16 v[136:139], v[84:87], v[156:159], v[152:155]
	v_exp_f32_e32 v227, v92
	v_mfma_f32_16x16x32_bf16 v[156:159], v[40:43], v[172:175], v[116:119]
	v_exp_f32_e32 v111, v93
	v_mfma_f32_16x16x32_bf16 v[152:155], v[84:87], v[172:175], v[168:171]
	v_exp_f32_e32 v229, v94
	v_mfma_f32_16x16x32_bf16 v[164:167], v[40:43], v[176:179], v[104:107]
	v_exp_f32_e32 v101, v95
	v_mfma_f32_16x16x32_bf16 v[160:163], v[84:87], v[176:179], v[160:163]
	s_nop 0
	v_cvt_pk_bf16_f32 v92, v3, v223
	v_cvt_pk_bf16_f32 v93, v225, v123
	v_cvt_pk_bf16_f32 v94, v227, v111
	v_cvt_pk_bf16_f32 v95, v229, v101
	v_exp_f32_e32 v97, v132
	s_waitcnt lgkmcnt(0)
	v_mfma_f32_16x16x32_bf16 v[172:175], v[40:43], v[238:241], v[180:183]
	v_exp_f32_e32 v231, v133
	v_mfma_f32_16x16x32_bf16 v[168:171], v[84:87], v[238:241], v[184:187]
	v_exp_f32_e32 v233, v134
	v_mfma_f32_16x16x32_bf16 v[176:179], v[40:43], v[242:245], v[80:83]
	v_exp_f32_e32 v79, v135
	v_mfma_f32_16x16x32_bf16 v[132:135], v[84:87], v[242:245], v[188:191]
	v_exp_f32_e32 v235, v112
	v_mfma_f32_16x16x32_bf16 v[184:187], v[40:43], v[246:249], v[68:71]
	v_exp_f32_e32 v67, v113
	v_mfma_f32_16x16x32_bf16 v[180:183], v[84:87], v[246:249], v[192:195]
	v_exp_f32_e32 v237, v114
	v_mfma_f32_16x16x32_bf16 v[192:195], v[40:43], v[250:253], v[56:59]
	v_exp_f32_e32 v55, v115
	v_mfma_f32_16x16x32_bf16 v[188:191], v[84:87], v[250:253], v[48:51]
	v_cvt_pk_bf16_f32 v112, v97, v231
	v_cvt_pk_bf16_f32 v113, v233, v79
	v_cvt_pk_bf16_f32 v114, v235, v67
	v_cvt_pk_bf16_f32 v115, v237, v55
	s_andn2_b64 vcc, exec, s[0:1]
	s_cbranch_vccnz .LBB0_865
	v_mov_b32_e32 v0, v210
	s_nop 0
	v_lshlrev_b32_e32 v0, 2, v0
	v_and_b32_e32 v0, 60, v0
	v_and_or_b32 v0, v212, 64, v0
	v_lshlrev_b32_e32 v0, 2, v0
	ds_bpermute_b32 v48, v0, v200
	ds_bpermute_b32 v50, v0, v200 offset:8
	ds_bpermute_b32 v51, v0, v200 offset:12
	ds_bpermute_b32 v49, v0, v200 offset:4
	ds_bpermute_b32 v56, v0, v201
	ds_bpermute_b32 v58, v0, v201 offset:8
	ds_bpermute_b32 v59, v0, v201 offset:12
	ds_bpermute_b32 v57, v0, v201 offset:4
	s_waitcnt lgkmcnt(5)
	v_pk_mul_f32 v[146:147], v[146:147], v[50:51]
	s_waitcnt lgkmcnt(4)
	v_pk_mul_f32 v[144:145], v[144:145], v[48:49]
	v_pk_mul_f32 v[150:151], v[150:151], v[50:51]
	v_pk_mul_f32 v[148:149], v[148:149], v[48:49]
	v_pk_mul_f32 v[158:159], v[158:159], v[50:51]
	v_pk_mul_f32 v[156:157], v[156:157], v[48:49]
	v_pk_mul_f32 v[166:167], v[166:167], v[50:51]
	v_pk_mul_f32 v[164:165], v[164:165], v[48:49]
	v_pk_mul_f32 v[174:175], v[174:175], v[50:51]
	v_pk_mul_f32 v[172:173], v[172:173], v[48:49]
	v_pk_mul_f32 v[178:179], v[178:179], v[50:51]
	v_pk_mul_f32 v[176:177], v[176:177], v[48:49]
	v_pk_mul_f32 v[186:187], v[186:187], v[50:51]
	v_pk_mul_f32 v[184:185], v[184:185], v[48:49]
	v_pk_mul_f32 v[194:195], v[194:195], v[50:51]
	v_pk_mul_f32 v[192:193], v[192:193], v[48:49]
	s_waitcnt lgkmcnt(1)
	v_pk_mul_f32 v[142:143], v[142:143], v[58:59]
	s_waitcnt lgkmcnt(0)
	v_pk_mul_f32 v[140:141], v[140:141], v[56:57]
	v_pk_mul_f32 v[138:139], v[138:139], v[58:59]
	v_pk_mul_f32 v[136:137], v[136:137], v[56:57]
	v_pk_mul_f32 v[154:155], v[154:155], v[58:59]
	v_pk_mul_f32 v[152:153], v[152:153], v[56:57]
	v_pk_mul_f32 v[162:163], v[162:163], v[58:59]
	v_pk_mul_f32 v[160:161], v[160:161], v[56:57]
	v_pk_mul_f32 v[170:171], v[170:171], v[58:59]
	v_pk_mul_f32 v[168:169], v[168:169], v[56:57]
	v_pk_mul_f32 v[134:135], v[134:135], v[58:59]
	v_pk_mul_f32 v[132:133], v[132:133], v[56:57]
	v_pk_mul_f32 v[182:183], v[182:183], v[58:59]
	v_pk_mul_f32 v[180:181], v[180:181], v[56:57]
	v_pk_mul_f32 v[190:191], v[190:191], v[58:59]
	v_pk_mul_f32 v[188:189], v[188:189], v[56:57]

.Lq1_h2_nok:
	global_load_dwordx4 v[4:7], v[202:203], off offset:-128
	global_load_dwordx4 v[12:15], v[202:203], off
	s_cmp_ge_u32 s89, s83
	s_cbranch_scc1 .Lq1_h2_pvonly
	ds_read_b128 v[36:39], v214
	ds_read_b128 v[40:43], v214 offset:64
	ds_read_b128 v[60:63], v214 offset:4352
	ds_read_b128 v[84:87], v214 offset:4416
	ds_read_b128 v[64:67], v214 offset:8704
	ds_read_b128 v[124:127], v214 offset:8768
	ds_read_b128 v[108:111], v214 offset:13056
	ds_read_b128 v[100:103], v214 offset:13120
	s_waitcnt lgkmcnt(7)
	v_mfma_f32_16x16x32_bf16 v[120:123], v[36:39], v[8:11], 0
	v_mfma_f32_16x16x32_bf16 v[36:39], v[36:39], v[20:23], 0
	s_waitcnt lgkmcnt(1)
	v_mfma_f32_16x16x32_bf16 v[116:119], v[60:63], v[8:11], 0
	v_mfma_f32_16x16x32_bf16 v[60:63], v[60:63], v[20:23], 0
	v_mfma_f32_16x16x32_bf16 v[96:99], v[64:67], v[8:11], 0
	v_mfma_f32_16x16x32_bf16 v[64:67], v[64:67], v[20:23], 0
	v_mfma_f32_16x16x32_bf16 v[104:107], v[108:111], v[8:11], 0
	v_mfma_f32_16x16x32_bf16 v[76:79], v[108:111], v[20:23], 0
	v_mfma_f32_16x16x32_bf16 v[128:131], v[40:43], v[16:19], v[120:123]
	v_mfma_f32_16x16x32_bf16 v[108:111], v[40:43], v[24:27], v[36:39]
	v_mfma_f32_16x16x32_bf16 v[36:39], v[84:87], v[16:19], v[116:119]
	v_mfma_f32_16x16x32_bf16 v[60:63], v[84:87], v[24:27], v[60:63]
	v_mfma_f32_16x16x32_bf16 v[120:123], v[124:127], v[16:19], v[96:99]
	v_mfma_f32_16x16x32_bf16 v[64:67], v[124:127], v[24:27], v[64:67]
	s_waitcnt lgkmcnt(0)
	v_mfma_f32_16x16x32_bf16 v[40:43], v[100:103], v[16:19], v[104:107]
	v_mfma_f32_16x16x32_bf16 v[84:87], v[100:103], v[24:27], v[76:79]
	s_cmp_eq_u32 s98, 0
	s_cbranch_scc1 .LBB0_875
	v_sub_f32_e32 v131, v131, v196
	v_sub_f32_e32 v130, v130, v196
	v_sub_f32_e32 v129, v129, v196
	v_sub_f32_e32 v128, v128, v196
	v_sub_f32_e32 v39, v39, v196
	v_sub_f32_e32 v38, v38, v196
	v_sub_f32_e32 v37, v37, v196
	v_sub_f32_e32 v36, v36, v196
	v_sub_f32_e32 v123, v123, v196
	v_sub_f32_e32 v122, v122, v196
	v_sub_f32_e32 v121, v121, v196
	v_sub_f32_e32 v120, v120, v196
	v_sub_f32_e32 v43, v43, v196
	v_sub_f32_e32 v42, v42, v196
	v_sub_f32_e32 v41, v41, v196
	v_sub_f32_e32 v40, v40, v196
	v_sub_f32_e32 v111, v111, v197
	v_sub_f32_e32 v110, v110, v197
	v_sub_f32_e32 v109, v109, v197
	v_sub_f32_e32 v108, v108, v197
	v_sub_f32_e32 v63, v63, v197
	v_sub_f32_e32 v62, v62, v197
	v_sub_f32_e32 v61, v61, v197
	v_sub_f32_e32 v60, v60, v197
	v_sub_f32_e32 v67, v67, v197
	v_sub_f32_e32 v66, v66, v197
	v_sub_f32_e32 v65, v65, v197
	v_sub_f32_e32 v64, v64, v197
	v_sub_f32_e32 v87, v87, v197
	v_sub_f32_e32 v86, v86, v197
	v_sub_f32_e32 v85, v85, v197
	v_sub_f32_e32 v84, v84, v197

.LBB0_877:
	v_max_f32_e32 v0, v128, v129
	v_max3_f32 v2, v131, v36, v37
	v_max3_f32 v0, v0, v130, v38
	v_max3_f32 v2, v2, v120, v121
	v_max3_f32 v0, v0, v39, v122
	v_max3_f32 v2, v2, v40, v41
	v_max3_f32 v0, v0, v123, v42
	v_max3_f32 v0, v0, v43, v2
	v_max_f32_e32 v2, v108, v109
	v_max3_f32 v3, v111, v60, v61
	v_max3_f32 v2, v2, v110, v62
	v_max3_f32 v3, v3, v64, v65
	v_max3_f32 v2, v2, v63, v66
	v_max3_f32 v3, v3, v84, v85
	v_max3_f32 v2, v2, v67, v86
	v_max3_f32 v2, v2, v87, v3
	v_max_f32_e32 v3, v0, v2
	v_cmp_lt_f32_e32 vcc, s74, v3
	s_cmp_lg_u64 vcc, 0
	s_cselect_b64 s[2:3], -1, 0
	s_cbranch_vccz .LBB0_879
	s_mov_b32 s98, 1
	v_and_b32_e32 v124, 64, v212
	v_xor_b32_e32 v3, 16, v212
	v_add_u32_e32 v124, 64, v124
	v_cmp_lt_i32_e32 vcc, v3, v124
	v_xor_b32_e32 v125, 32, v212
	s_nop 0
	v_cndmask_b32_e32 v3, v212, v3, vcc
	v_lshlrev_b32_e32 v3, 2, v3
	ds_bpermute_b32 v126, v3, v0
	ds_bpermute_b32 v3, v3, v2
	v_cmp_lt_i32_e32 vcc, v125, v124
	v_max_f32_e32 v2, v2, v2
	v_max_f32_e32 v0, v0, v0
	v_cndmask_b32_e32 v124, v212, v125, vcc
	s_waitcnt lgkmcnt(0)
	v_max_f32_e32 v3, v3, v3
	v_lshlrev_b32_e32 v124, 2, v124
	v_max_f32_e32 v125, v126, v126
	v_max_f32_e32 v2, v2, v3
	v_max_f32_e32 v0, v0, v125
	ds_bpermute_b32 v3, v124, v2
	ds_bpermute_b32 v125, v124, v0
	s_waitcnt lgkmcnt(1)
	v_max_f32_e32 v3, v3, v3
	s_waitcnt lgkmcnt(0)
	v_max_f32_e32 v124, v125, v125
	v_max_f32_e32 v2, v2, v3
	v_max_f32_e32 v0, v0, v124
	v_cmp_lt_f32_e32 vcc, s74, v2
	s_nop 1
	v_cndmask_b32_e32 v3, 0, v2, vcc
	v_cmp_lt_f32_e32 vcc, s74, v0
	v_exp_f32_e64 v201, -v3
	v_sub_f32_e32 v108, v108, v3
	v_cndmask_b32_e32 v2, 0, v0, vcc
	v_exp_f32_e64 v200, -v2
	v_sub_f32_e32 v128, v128, v2
	v_sub_f32_e32 v129, v129, v2
	v_sub_f32_e32 v130, v130, v2
	v_sub_f32_e32 v131, v131, v2
	v_sub_f32_e32 v36, v36, v2
	v_sub_f32_e32 v37, v37, v2
	v_sub_f32_e32 v38, v38, v2
	v_sub_f32_e32 v39, v39, v2
	v_sub_f32_e32 v120, v120, v2
	v_sub_f32_e32 v121, v121, v2
	v_sub_f32_e32 v122, v122, v2
	v_sub_f32_e32 v123, v123, v2
	v_sub_f32_e32 v40, v40, v2
	v_sub_f32_e32 v41, v41, v2
	v_sub_f32_e32 v42, v42, v2
	v_sub_f32_e32 v43, v43, v2
	v_pk_add_f32 v[196:197], v[196:197], v[2:3]
	v_sub_f32_e32 v109, v109, v3
	v_sub_f32_e32 v110, v110, v3
	v_sub_f32_e32 v111, v111, v3
	v_sub_f32_e32 v60, v60, v3
	v_sub_f32_e32 v61, v61, v3
	v_sub_f32_e32 v62, v62, v3
	v_sub_f32_e32 v63, v63, v3
	v_sub_f32_e32 v64, v64, v3
	v_sub_f32_e32 v65, v65, v3
	v_sub_f32_e32 v66, v66, v3
	v_sub_f32_e32 v67, v67, v3
	v_sub_f32_e32 v84, v84, v3
	v_sub_f32_e32 v85, v85, v3
	v_sub_f32_e32 v86, v86, v3
	v_sub_f32_e32 v87, v87, v3
	v_pk_mul_f32 v[198:199], v[198:199], v[200:201]
.LBB0_879:
	ds_read_b64_tr_b16 v[124:125], v215 offset:53248
	ds_read_b64_tr_b16 v[100:101], v215 offset:53280
	ds_read_b64_tr_b16 v[116:117], v215 offset:53312
	ds_read_b64_tr_b16 v[96:97], v215 offset:53344
	ds_read_b64_tr_b16 v[126:127], v215 offset:57856
	ds_read_b64_tr_b16 v[102:103], v215 offset:57888
	ds_read_b64_tr_b16 v[118:119], v215 offset:57920
	ds_read_b64_tr_b16 v[98:99], v215 offset:57952
	v_exp_f32_e32 v2, v128
	s_waitcnt lgkmcnt(3)
	v_mfma_f32_16x16x32_bf16 v[104:107], v[44:47], v[124:127], v[144:147]
	v_exp_f32_e32 v222, v129
	v_mfma_f32_16x16x32_bf16 v[124:127], v[92:95], v[124:127], v[140:143]
	ds_read_b64_tr_b16 v[238:239], v215 offset:53376
	ds_read_b64_tr_b16 v[242:243], v215 offset:53408
	ds_read_b64_tr_b16 v[246:247], v215 offset:53440
	ds_read_b64_tr_b16 v[250:251], v215 offset:53472
	ds_read_b64_tr_b16 v[240:241], v215 offset:57984
	ds_read_b64_tr_b16 v[244:245], v215 offset:58016
	ds_read_b64_tr_b16 v[248:249], v215 offset:58048
	ds_read_b64_tr_b16 v[252:253], v215 offset:58080
	v_exp_f32_e32 v224, v130
	s_waitcnt lgkmcnt(8)
	v_mfma_f32_16x16x32_bf16 v[148:151], v[44:47], v[100:103], v[148:151]
	v_exp_f32_e32 v142, v131
	v_mfma_f32_16x16x32_bf16 v[100:103], v[92:95], v[100:103], v[136:139]
	v_exp_f32_e32 v226, v36
	v_mfma_f32_16x16x32_bf16 v[156:159], v[44:47], v[116:119], v[156:159]
	v_exp_f32_e32 v138, v37
	v_mfma_f32_16x16x32_bf16 v[76:79], v[92:95], v[116:119], v[152:155]
	v_exp_f32_e32 v228, v38
	v_mfma_f32_16x16x32_bf16 v[164:167], v[44:47], v[96:99], v[164:167]
	v_exp_f32_e32 v154, v39
	v_mfma_f32_16x16x32_bf16 v[96:99], v[92:95], v[96:99], v[160:163]
	v_cvt_pk_bf16_f32 v36, v2, v222
	v_cvt_pk_bf16_f32 v37, v224, v142
	v_cvt_pk_bf16_f32 v38, v226, v138
	v_cvt_pk_bf16_f32 v39, v228, v154
	v_exp_f32_e32 v160, v120
	s_waitcnt lgkmcnt(0)
	v_mfma_f32_16x16x32_bf16 v[52:55], v[44:47], v[238:241], v[172:175]
	v_exp_f32_e32 v230, v121
	v_mfma_f32_16x16x32_bf16 v[68:71], v[92:95], v[238:241], v[168:171]
	v_exp_f32_e32 v232, v122
	v_mfma_f32_16x16x32_bf16 v[176:179], v[44:47], v[242:245], v[176:179]
	v_exp_f32_e32 v170, v123
	v_mfma_f32_16x16x32_bf16 v[48:51], v[92:95], v[242:245], v[132:135]
	ds_read_b64_tr_b16 v[120:121], v215 offset:62464
	ds_read_b64_tr_b16 v[116:117], v215 offset:62496
	ds_read_b64_tr_b16 v[88:89], v215 offset:62528
	ds_read_b64_tr_b16 v[80:81], v215 offset:62560
	ds_read_b64_tr_b16 v[122:123], v216 offset:13824
	ds_read_b64_tr_b16 v[118:119], v216 offset:13856
	ds_read_b64_tr_b16 v[90:91], v216 offset:13888
	ds_read_b64_tr_b16 v[82:83], v216 offset:13920
	v_exp_f32_e32 v234, v40
	v_mfma_f32_16x16x32_bf16 v[184:187], v[44:47], v[246:249], v[184:187]
	v_exp_f32_e32 v134, v41
	v_mfma_f32_16x16x32_bf16 v[56:59], v[92:95], v[246:249], v[180:183]
	v_exp_f32_e32 v236, v42
	v_mfma_f32_16x16x32_bf16 v[192:195], v[44:47], v[250:253], v[192:195]
	v_exp_f32_e32 v182, v43
	v_mfma_f32_16x16x32_bf16 v[188:191], v[92:95], v[250:253], v[188:191]
	v_cvt_pk_bf16_f32 v40, v160, v230
	v_cvt_pk_bf16_f32 v41, v232, v170
	v_cvt_pk_bf16_f32 v42, v234, v134
	v_cvt_pk_bf16_f32 v43, v236, v182
	v_exp_f32_e32 v3, v108
	s_waitcnt lgkmcnt(0)
	v_mfma_f32_16x16x32_bf16 v[128:131], v[72:75], v[120:123], v[104:107]
	v_exp_f32_e32 v223, v109
	v_mfma_f32_16x16x32_bf16 v[120:123], v[112:115], v[120:123], v[124:127]
	ds_read_b64_tr_b16 v[238:239], v215 offset:62592
	ds_read_b64_tr_b16 v[242:243], v215 offset:62624
	ds_read_b64_tr_b16 v[246:247], v215 offset:62656
	ds_read_b64_tr_b16 v[250:251], v215 offset:62688
	ds_read_b64_tr_b16 v[240:241], v216 offset:13952
	ds_read_b64_tr_b16 v[244:245], v216 offset:13984
	ds_read_b64_tr_b16 v[248:249], v216 offset:14016
	ds_read_b64_tr_b16 v[252:253], v216 offset:14048
	v_exp_f32_e32 v225, v110
	v_mfma_f32_16x16x32_bf16 v[124:127], v[72:75], v[116:119], v[148:151]
	v_exp_f32_e32 v143, v111
	v_mfma_f32_16x16x32_bf16 v[108:111], v[112:115], v[116:119], v[100:103]
	v_exp_f32_e32 v227, v60
	v_mfma_f32_16x16x32_bf16 v[116:119], v[72:75], v[88:91], v[156:159]
	v_exp_f32_e32 v139, v61
	v_mfma_f32_16x16x32_bf16 v[100:103], v[112:115], v[88:91], v[76:79]
	v_exp_f32_e32 v229, v62
	v_mfma_f32_16x16x32_bf16 v[104:107], v[72:75], v[80:83], v[164:167]
	v_exp_f32_e32 v155, v63
	v_mfma_f32_16x16x32_bf16 v[96:99], v[112:115], v[80:83], v[96:99]
	s_nop 0
	v_cvt_pk_bf16_f32 v60, v3, v223
	v_cvt_pk_bf16_f32 v61, v225, v143
	v_cvt_pk_bf16_f32 v62, v227, v139
	v_cvt_pk_bf16_f32 v63, v229, v155
	v_exp_f32_e32 v161, v64
	s_waitcnt lgkmcnt(0)
	v_mfma_f32_16x16x32_bf16 v[88:91], v[72:75], v[238:241], v[52:55]
	v_exp_f32_e32 v231, v65
	v_mfma_f32_16x16x32_bf16 v[76:79], v[112:115], v[238:241], v[68:71]
	v_exp_f32_e32 v233, v66
	v_mfma_f32_16x16x32_bf16 v[80:83], v[72:75], v[242:245], v[176:179]
	v_exp_f32_e32 v171, v67
	v_mfma_f32_16x16x32_bf16 v[64:67], v[112:115], v[242:245], v[48:51]
	v_exp_f32_e32 v235, v84
	v_mfma_f32_16x16x32_bf16 v[68:71], v[72:75], v[246:249], v[184:187]
	v_exp_f32_e32 v135, v85
	v_mfma_f32_16x16x32_bf16 v[52:55], v[112:115], v[246:249], v[56:59]
	v_exp_f32_e32 v237, v86
	v_mfma_f32_16x16x32_bf16 v[56:59], v[72:75], v[250:253], v[192:195]
	v_exp_f32_e32 v183, v87
	v_mfma_f32_16x16x32_bf16 v[48:51], v[112:115], v[250:253], v[188:191]
	v_cvt_pk_bf16_f32 v84, v161, v231
	v_cvt_pk_bf16_f32 v85, v233, v171
	v_cvt_pk_bf16_f32 v86, v235, v135
	v_cvt_pk_bf16_f32 v87, v237, v183
	s_andn2_b64 vcc, exec, s[2:3]
	s_cbranch_vccnz .LBB0_881
	v_mov_b32_e32 v0, v210
	s_nop 0
	v_lshlrev_b32_e32 v0, 2, v0
	v_and_b32_e32 v0, 60, v0
	v_and_or_b32 v0, v212, 64, v0
	v_lshlrev_b32_e32 v0, 2, v0
	ds_bpermute_b32 v188, v0, v200
	ds_bpermute_b32 v190, v0, v200 offset:8
	ds_bpermute_b32 v191, v0, v200 offset:12
	ds_bpermute_b32 v189, v0, v200 offset:4
	ds_bpermute_b32 v192, v0, v201
	ds_bpermute_b32 v194, v0, v201 offset:8
	ds_bpermute_b32 v195, v0, v201 offset:12
	ds_bpermute_b32 v193, v0, v201 offset:4
	s_waitcnt lgkmcnt(5)
	v_pk_mul_f32 v[130:131], v[130:131], v[190:191]
	s_waitcnt lgkmcnt(4)
	v_pk_mul_f32 v[128:129], v[128:129], v[188:189]
	v_pk_mul_f32 v[126:127], v[126:127], v[190:191]
	v_pk_mul_f32 v[124:125], v[124:125], v[188:189]
	v_pk_mul_f32 v[118:119], v[118:119], v[190:191]
	v_pk_mul_f32 v[116:117], v[116:117], v[188:189]
	v_pk_mul_f32 v[106:107], v[106:107], v[190:191]
	v_pk_mul_f32 v[104:105], v[104:105], v[188:189]
	v_pk_mul_f32 v[90:91], v[90:91], v[190:191]
	v_pk_mul_f32 v[88:89], v[88:89], v[188:189]
	v_pk_mul_f32 v[82:83], v[82:83], v[190:191]
	v_pk_mul_f32 v[80:81], v[80:81], v[188:189]
	v_pk_mul_f32 v[70:71], v[70:71], v[190:191]
	v_pk_mul_f32 v[68:69], v[68:69], v[188:189]
	v_pk_mul_f32 v[58:59], v[58:59], v[190:191]
	v_pk_mul_f32 v[56:57], v[56:57], v[188:189]
	s_waitcnt lgkmcnt(1)
	v_pk_mul_f32 v[122:123], v[122:123], v[194:195]
	s_waitcnt lgkmcnt(0)
	v_pk_mul_f32 v[120:121], v[120:121], v[192:193]
	v_pk_mul_f32 v[110:111], v[110:111], v[194:195]
	v_pk_mul_f32 v[108:109], v[108:109], v[192:193]
	v_pk_mul_f32 v[102:103], v[102:103], v[194:195]
	v_pk_mul_f32 v[100:101], v[100:101], v[192:193]
	v_pk_mul_f32 v[98:99], v[98:99], v[194:195]
	v_pk_mul_f32 v[96:97], v[96:97], v[192:193]
	v_pk_mul_f32 v[78:79], v[78:79], v[194:195]
	v_pk_mul_f32 v[76:77], v[76:77], v[192:193]
	v_pk_mul_f32 v[66:67], v[66:67], v[194:195]
	v_pk_mul_f32 v[64:65], v[64:65], v[192:193]
	v_pk_mul_f32 v[54:55], v[54:55], v[194:195]
	v_pk_mul_f32 v[52:53], v[52:53], v[192:193]
	v_pk_mul_f32 v[50:51], v[50:51], v[194:195]
	v_pk_mul_f32 v[48:49], v[48:49], v[192:193]
